# G2 gate tail GEMM: the two gate loads issued ahead of the K-split reduction instead of after it
# baseline (speedup 1.0000x reference)
.LBB0_772:
	s_and_b32 s20, s16, 0x70
	v_or_b32_e32 v2, s20, v22
	s_movk_i32 s22, 0xc00
	v_mad_u64_u32 v[92:93], s[20:21], v2, s22, v[0:1]
	s_and_b32 s20, s17, 0xffffffc0
	s_nop 0
	v_or_b32_e32 v6, s20, v18
	v_mad_i64_i32 v[116:117], s[22:23], v6, s22, v[4:5]
	v_lshl_add_u64 v[64:65], v[116:117], 0, s[10:11]
	v_add_co_u32_e32 v72, vcc, 0xc000, v64
	s_mov_b32 s21, 0x18000
	s_nop 0
	v_addc_co_u32_e32 v73, vcc, 0, v65, vcc
	v_add_co_u32_e32 v80, vcc, s21, v64
	v_lshl_add_u64 v[56:57], v[92:93], 0, s[10:11]
	s_nop 0
	v_addc_co_u32_e32 v81, vcc, 0, v65, vcc
	v_add_co_u32_e32 v88, vcc, 0x24000, v64
	v_lshl_add_u64 v[100:101], s[4:5], 1, v[116:117]
	s_nop 0
	v_addc_co_u32_e32 v89, vcc, 0, v65, vcc
	global_load_dwordx4 v[6:9], v[56:57], off
	global_load_dwordx4 v[10:13], v[56:57], off offset:64
	global_load_dwordx4 v[14:17], v[64:65], off
	global_load_dwordx4 v[24:27], v[64:65], off offset:64
	global_load_dwordx4 v[28:31], v[72:73], off
	global_load_dwordx4 v[32:35], v[72:73], off offset:64
	global_load_dwordx4 v[36:39], v[80:81], off
	global_load_dwordx4 v[40:43], v[80:81], off offset:64
	global_load_dwordx4 v[44:47], v[88:89], off
	global_load_dwordx4 v[48:51], v[88:89], off offset:64
	global_load_dwordx4 v[52:55], v[56:57], off offset:128
	s_nop 0
	global_load_dwordx4 v[56:59], v[56:57], off offset:192
	s_nop 0
	global_load_dwordx4 v[60:63], v[64:65], off offset:128
	s_nop 0
	global_load_dwordx4 v[64:67], v[64:65], off offset:192
	s_nop 0
	global_load_dwordx4 v[68:71], v[72:73], off offset:128
	s_nop 0
	global_load_dwordx4 v[72:75], v[72:73], off offset:192
	s_nop 0
	global_load_dwordx4 v[76:79], v[80:81], off offset:128
	s_nop 0
	global_load_dwordx4 v[80:83], v[80:81], off offset:192
	s_nop 0
	global_load_dwordx4 v[84:87], v[88:89], off offset:128
	s_nop 0
	global_load_dwordx4 v[88:91], v[88:89], off offset:192
	s_mov_b32 s22, 0xc000
	v_add_co_u32_e32 v96, vcc, s22, v100
	s_mov_b32 s23, 0x24000
	s_nop 0
	v_addc_co_u32_e32 v97, vcc, 0, v101, vcc
	v_add_co_u32_e32 v102, vcc, s21, v100
	v_lshl_add_u64 v[124:125], s[8:9], 1, v[116:117]
	s_nop 0
	v_addc_co_u32_e32 v103, vcc, 0, v101, vcc
	v_add_co_u32_e32 v104, vcc, s23, v100
	v_lshl_add_u64 v[112:113], s[0:1], 1, v[92:93]
	s_nop 0
	v_addc_co_u32_e32 v105, vcc, 0, v101, vcc
	v_add_co_u32_e32 v120, vcc, s22, v124
	global_load_dwordx4 v[92:95], v[100:101], off
	s_nop 0
	global_load_dwordx4 v[96:99], v[96:97], off
	v_addc_co_u32_e32 v121, vcc, 0, v125, vcc
	v_add_co_u32_e32 v126, vcc, s21, v124
	global_load_dwordx4 v[100:103], v[102:103], off
	s_nop 0
	global_load_dwordx4 v[104:107], v[104:105], off
	s_nop 0
	global_load_dwordx4 v[108:111], v[112:113], off offset:2048
	s_nop 0
	global_load_dwordx4 v[112:115], v[112:113], off offset:2112
	v_addc_co_u32_e32 v127, vcc, 0, v125, vcc
	v_add_co_u32_e32 v128, vcc, s23, v124
	global_load_dwordx4 v[116:119], v[124:125], off
	s_nop 0
	global_load_dwordx4 v[120:123], v[120:121], off
	v_addc_co_u32_e32 v129, vcc, 0, v125, vcc
	global_load_dwordx4 v[124:127], v[126:127], off
	s_nop 0
	global_load_dwordx4 v[128:131], v[128:129], off
	s_waitcnt vmcnt(0)
	v_mfma_f32_16x16x32_bf16 v[14:17], v[14:17], v[6:9], 0
	s_andn2_b64 vcc, exec, s[2:3]
	v_mfma_f32_16x16x32_bf16 v[28:31], v[28:31], v[6:9], 0
	v_mfma_f32_16x16x32_bf16 v[36:39], v[36:39], v[6:9], 0
	v_mfma_f32_16x16x32_bf16 v[6:9], v[44:47], v[6:9], 0
	v_mfma_f32_16x16x32_bf16 v[14:17], v[24:27], v[10:13], v[14:17]
	v_mfma_f32_16x16x32_bf16 v[24:27], v[32:35], v[10:13], v[28:31]
	v_mfma_f32_16x16x32_bf16 v[28:31], v[40:43], v[10:13], v[36:39]
	v_mfma_f32_16x16x32_bf16 v[6:9], v[48:51], v[10:13], v[6:9]
	v_mfma_f32_16x16x32_bf16 v[10:13], v[60:63], v[52:55], v[14:17]
	v_mfma_f32_16x16x32_bf16 v[14:17], v[68:71], v[52:55], v[24:27]
	v_mfma_f32_16x16x32_bf16 v[24:27], v[76:79], v[52:55], v[28:31]
	v_mfma_f32_16x16x32_bf16 v[28:31], v[92:95], v[108:111], 0
	v_mfma_f32_16x16x32_bf16 v[10:13], v[64:67], v[56:59], v[10:13]
	v_mfma_f32_16x16x32_bf16 v[32:35], v[96:99], v[108:111], 0
	v_mfma_f32_16x16x32_bf16 v[36:39], v[100:103], v[108:111], 0
	s_nop 5
	ds_write_b128 v21, v[10:13]
	v_mfma_f32_16x16x32_bf16 v[28:31], v[116:119], v[112:115], v[28:31]
	v_mfma_f32_16x16x32_bf16 v[6:9], v[84:87], v[52:55], v[6:9]
	v_mfma_f32_16x16x32_bf16 v[14:17], v[72:75], v[56:59], v[14:17]
	v_mfma_f32_16x16x32_bf16 v[10:13], v[120:123], v[112:115], v[32:35]
	s_nop 4
	ds_write_b128 v21, v[28:31] offset:32768
	s_nop 0
	ds_write_b128 v21, v[14:17] offset:1024
	ds_write_b128 v21, v[10:13] offset:33792
	v_mfma_f32_16x16x32_bf16 v[24:27], v[80:83], v[56:59], v[24:27]
	v_mfma_f32_16x16x32_bf16 v[40:43], v[104:107], v[108:111], 0
	v_mfma_f32_16x16x32_bf16 v[10:13], v[124:127], v[112:115], v[36:39]
	v_mfma_f32_16x16x32_bf16 v[6:9], v[88:91], v[56:59], v[6:9]
	s_nop 4
	ds_write_b128 v21, v[24:27] offset:2048
	s_nop 0
	ds_write_b128 v21, v[10:13] offset:34816
	ds_write_b128 v21, v[6:9] offset:3072
	v_mfma_f32_16x16x32_bf16 v[6:9], v[128:131], v[112:115], v[40:43]
	s_nop 7
	ds_write_b128 v21, v[6:9] offset:35840
	s_waitcnt lgkmcnt(0)
	s_barrier
	s_cbranch_vccnz .LBB0_771
	ds_read_b128 v[6:9], v19
	ds_read_b128 v[10:13], v19 offset:32768
	ds_read_b128 v[14:17], v19 offset:4096
	v_lshlrev_b32_e32 v2, 11, v2
	v_lshl_add_u64 v[30:31], s[68:69], 0, v[2:3]
	v_add_u32_e32 v96, s20, v20
	v_ashrrev_i32_e32 v97, 31, v96
	v_lshlrev_b64 v[96:97], 1, v[96:97]
	v_lshl_add_u64 v[98:99], s[36:37], 0, v[2:3]
	v_lshl_add_u64 v[98:99], v[98:99], 0, v[96:97]
	global_load_dwordx2 v[102:103], v[98:99], off
	v_readlane_b32 vcc_lo, v252, 60
	v_readlane_b32 vcc_hi, v252, 61
	s_nop 1
	v_lshl_add_u64 v[100:101], vcc, 0, v[2:3]
	v_lshl_add_u64 v[100:101], v[100:101], 0, v[96:97]
	global_load_dwordx2 v[104:105], v[100:101], off
	s_waitcnt lgkmcnt(0)
	v_pk_add_f32 v[16:17], v[8:9], v[16:17]
	v_pk_add_f32 v[14:15], v[6:7], v[14:15]
	ds_read_b128 v[6:9], v19 offset:36864
	s_waitcnt lgkmcnt(0)
	v_pk_add_f32 v[12:13], v[12:13], v[8:9]
	v_pk_add_f32 v[10:11], v[10:11], v[6:7]
	ds_read_b128 v[6:9], v19 offset:8192
	s_waitcnt lgkmcnt(0)
	v_pk_add_f32 v[16:17], v[16:17], v[8:9]
	v_pk_add_f32 v[14:15], v[14:15], v[6:7]
	ds_read_b128 v[6:9], v19 offset:40960
	s_waitcnt lgkmcnt(0)
	v_pk_add_f32 v[12:13], v[12:13], v[8:9]
	v_pk_add_f32 v[10:11], v[10:11], v[6:7]
	ds_read_b128 v[6:9], v19 offset:12288
	s_waitcnt lgkmcnt(0)
	v_pk_add_f32 v[16:17], v[16:17], v[8:9]
	v_pk_add_f32 v[14:15], v[14:15], v[6:7]
	ds_read_b128 v[6:9], v19 offset:45056
	s_waitcnt lgkmcnt(0)
	v_pk_add_f32 v[12:13], v[12:13], v[8:9]
	v_pk_add_f32 v[10:11], v[10:11], v[6:7]
	ds_read_b128 v[6:9], v19 offset:16384
	s_waitcnt lgkmcnt(0)
	v_pk_add_f32 v[16:17], v[16:17], v[8:9]
	v_pk_add_f32 v[14:15], v[14:15], v[6:7]
	ds_read_b128 v[6:9], v19 offset:49152
	s_waitcnt lgkmcnt(0)
	v_pk_add_f32 v[12:13], v[12:13], v[8:9]
	v_pk_add_f32 v[10:11], v[10:11], v[6:7]
	ds_read_b128 v[6:9], v19 offset:20480
	s_waitcnt lgkmcnt(0)
	v_pk_add_f32 v[16:17], v[16:17], v[8:9]
	v_pk_add_f32 v[14:15], v[14:15], v[6:7]
	ds_read_b128 v[6:9], v19 offset:53248
	s_waitcnt lgkmcnt(0)
	v_pk_add_f32 v[12:13], v[12:13], v[8:9]
	v_pk_add_f32 v[10:11], v[10:11], v[6:7]
	ds_read_b128 v[6:9], v19 offset:24576
	s_waitcnt lgkmcnt(0)
	v_pk_add_f32 v[16:17], v[16:17], v[8:9]
	v_pk_add_f32 v[14:15], v[14:15], v[6:7]
	ds_read_b128 v[6:9], v19 offset:57344
	s_waitcnt lgkmcnt(0)
	v_pk_add_f32 v[24:25], v[12:13], v[8:9]
	v_pk_add_f32 v[26:27], v[10:11], v[6:7]
	ds_read_b128 v[6:9], v19 offset:28672
	s_waitcnt lgkmcnt(0)
	v_pk_add_f32 v[6:7], v[14:15], v[6:7]
	ds_read_b128 v[12:15], v19 offset:61440
	v_pk_add_f32 v[8:9], v[16:17], v[8:9]
	v_lshl_add_u64 v[16:17], s[36:37], 0, v[2:3]
	s_waitcnt lgkmcnt(0)
	v_pk_add_f32 v[10:11], v[24:25], v[14:15]
	v_add_u32_e32 v14, s20, v20
	v_readlane_b32 s20, v252, 60
	v_ashrrev_i32_e32 v15, 31, v14
	v_readlane_b32 s21, v252, 61
	v_pk_add_f32 v[12:13], v[26:27], v[12:13]
	v_lshlrev_b64 v[24:25], 1, v[14:15]
	v_lshl_add_u64 v[26:27], s[20:21], 0, v[2:3]
	v_lshl_add_u64 v[14:15], v[16:17], 0, v[24:25]
	v_lshl_add_u64 v[26:27], v[26:27], 0, v[24:25]
	v_lshl_add_u64 v[24:25], v[30:31], 0, v[24:25]
	s_waitcnt vmcnt(1)
	v_lshlrev_b32_e32 v14, 16, v102
	v_and_b32_e32 v15, 0xffff0000, v102
	s_waitcnt vmcnt(0)
	v_lshlrev_b32_e32 v28, 16, v104
	v_and_b32_e32 v29, 0xffff0000, v104
	v_lshlrev_b32_e32 v26, 16, v105
	v_and_b32_e32 v27, 0xffff0000, v105
	v_lshlrev_b32_e32 v16, 16, v103
	v_and_b32_e32 v17, 0xffff0000, v103
	v_pk_mul_f32 v[12:13], v[12:13], v[28:29]
	v_pk_mul_f32 v[10:11], v[10:11], v[26:27]
	v_pk_fma_f32 v[6:7], v[6:7], v[14:15], v[12:13]
	v_pk_fma_f32 v[8:9], v[8:9], v[16:17], v[10:11]
	v_cvt_pk_bf16_f32 v6, v6, v7
	v_cvt_pk_bf16_f32 v7, v8, v9
	global_store_dwordx2 v[24:25], v[6:7], off
	s_branch .LBB0_771
